# v104 plus SwiGLU epilogues of both gate-up GEMMs rewritten with packed f32 mul/add (same operations and order, 128 fewer VALU instructions per wave per tile)
# baseline (speedup 1.0000x reference)
; __device__ __forceinline__ unsigned cvt_pk_bf16(float lo, float hi) { unsigned r; asm volatile("v_cvt_pk_bf16_f32 %0, %1, %2" : "=v"(r) : "v"(lo), "v"(hi)); return r; }
; __device__ __forceinline__ float silu_mul(float g, float u) {
;     const float e = __builtin_amdgcn_exp2f(g * -1.4426950408889634f);
;     return g * __builtin_amdgcn_rcpf(1.0f + e) * u;
; }
;     __device__ __forceinline__ void operator()(const f32x4 (&acc)[2][2][4][2], const Unit& u, int wr, int wc, int fr, int fq, const float (&rv)[8]) const {
;         const int row0 = u.pm * BM + wr * 64 + fr, col0 = u.pn * HALF + wc * 32 + 8 * fq;
; #pragma unroll
;         for (int ai = 0; ai < 2; ++ai)
; #pragma unroll
;             for (int m = 0; m < 4; ++m) {
;                 bf16_t* rowp = O + (size_t)(row0 + ai * HALF + m * 16) * ldc + col0;
;                 const float r = rv[ai * 4 + m];
;                 const f32x4 g0 = acc[ai][0][m][0] * r, g1 = acc[ai][0][m][1] * r, u0 = acc[ai][1][m][0] * r, u1 = acc[ai][1][m][1] * r;
;                 u32x4 w;
;                 w.x = cvt_pk_bf16(silu_mul(g0[0], u0[0]), silu_mul(g0[1], u0[1]));
;                 w.y = cvt_pk_bf16(silu_mul(g0[2], u0[2]), silu_mul(g0[3], u0[3]));
;                 w.z = cvt_pk_bf16(silu_mul(g1[0], u1[0]), silu_mul(g1[1], u1[1]));
;                 w.w = cvt_pk_bf16(silu_mul(g1[2], u1[2]), silu_mul(g1[3], u1[3]));
;                 *(u32x4*)rowp = w;
.LBB0_105:
	s_waitcnt vmcnt(0)
	s_mov_b32 s98, 0xbfb8aa3b
	s_mov_b32 s99, 0xbfb8aa3b
	s_mov_b32 s100, 1.0
	s_mov_b32 s101, 1.0
	s_nop 7
	s_nop 7
	v_pk_mul_f32 v[124:125], v[158:159], v[124:125] op_sel_hi:[0,1]
	v_pk_mul_f32 v[116:117], v[158:159], v[116:117] op_sel_hi:[0,1]
	v_pk_mul_f32 v[126:127], v[158:159], v[126:127] op_sel_hi:[0,1]
	v_pk_mul_f32 v[118:119], v[158:159], v[118:119] op_sel_hi:[0,1]
	v_pk_mul_f32 v[246:247], v[124:125], s[98:99]
	v_pk_mul_f32 v[248:249], v[126:127], s[98:99]
	v_exp_f32_e32 v246, v246
	v_exp_f32_e32 v247, v247
	v_exp_f32_e32 v248, v248
	v_exp_f32_e32 v249, v249
	v_pk_add_f32 v[246:247], v[246:247], s[100:101]
	v_pk_add_f32 v[248:249], v[248:249], s[100:101]
	v_rcp_f32_e32 v246, v246
	v_rcp_f32_e32 v247, v247
	v_rcp_f32_e32 v248, v248
	v_rcp_f32_e32 v249, v249
	v_pk_mul_f32 v[124:125], v[124:125], v[246:247]
	v_pk_mul_f32 v[126:127], v[126:127], v[248:249]
	v_pk_mul_f32 v[124:125], v[124:125], v[116:117]
	v_pk_mul_f32 v[126:127], v[126:127], v[118:119]
	v_lshl_or_b32 v162, s87, 7, v153
	v_lshl_add_u32 v164, s4, 8, v137
	v_ashrrev_i32_e32 v163, 31, v162
	v_mov_b64_e32 v[160:161], s[14:15]
	v_mad_i64_i32 v[166:167], s[10:11], v164, s86, v[160:161]
	v_lshlrev_b64 v[162:163], 1, v[162:163]
	v_lshl_add_u64 v[166:167], v[166:167], 0, v[162:163]
	v_pk_mul_f32 v[120:121], v[158:159], v[120:121] op_sel_hi:[0,1]
	v_pk_mul_f32 v[112:113], v[158:159], v[112:113] op_sel_hi:[0,1]
	v_pk_mul_f32 v[122:123], v[158:159], v[122:123] op_sel_hi:[0,1]
	v_pk_mul_f32 v[114:115], v[158:159], v[114:115] op_sel_hi:[0,1]
	v_pk_mul_f32 v[246:247], v[120:121], s[98:99]
	v_pk_mul_f32 v[248:249], v[122:123], s[98:99]
	v_exp_f32_e32 v246, v246
	v_exp_f32_e32 v247, v247
	v_exp_f32_e32 v248, v248
	v_exp_f32_e32 v249, v249
	v_pk_add_f32 v[246:247], v[246:247], s[100:101]
	v_pk_add_f32 v[248:249], v[248:249], s[100:101]
	v_rcp_f32_e32 v246, v246
	v_rcp_f32_e32 v247, v247
	v_rcp_f32_e32 v248, v248
	v_rcp_f32_e32 v249, v249
	v_pk_mul_f32 v[120:121], v[120:121], v[246:247]
	v_pk_mul_f32 v[122:123], v[122:123], v[248:249]
	v_pk_mul_f32 v[120:121], v[120:121], v[112:113]
	v_pk_mul_f32 v[122:123], v[122:123], v[114:115]
	v_cvt_pk_bf16_f32 v112, v124, v125
	v_cvt_pk_bf16_f32 v113, v126, v127
	v_cvt_pk_bf16_f32 v114, v120, v121
	v_cvt_pk_bf16_f32 v115, v122, v123
	global_store_dwordx4 v[166:167], v[112:115], off
	v_pk_mul_f32 v[108:109], v[156:157], v[108:109] op_sel_hi:[0,1]
	v_pk_mul_f32 v[100:101], v[156:157], v[100:101] op_sel_hi:[0,1]
	v_pk_mul_f32 v[110:111], v[156:157], v[110:111] op_sel_hi:[0,1]
	v_pk_mul_f32 v[102:103], v[156:157], v[102:103] op_sel_hi:[0,1]
	v_pk_mul_f32 v[246:247], v[108:109], s[98:99]
	v_pk_mul_f32 v[248:249], v[110:111], s[98:99]
	v_exp_f32_e32 v246, v246
	v_exp_f32_e32 v247, v247
	v_exp_f32_e32 v248, v248
	v_exp_f32_e32 v249, v249
	v_pk_add_f32 v[246:247], v[246:247], s[100:101]
	v_pk_add_f32 v[248:249], v[248:249], s[100:101]
	v_rcp_f32_e32 v246, v246
	v_rcp_f32_e32 v247, v247
	v_rcp_f32_e32 v248, v248
	v_rcp_f32_e32 v249, v249
	v_pk_mul_f32 v[108:109], v[108:109], v[246:247]
	v_pk_mul_f32 v[110:111], v[110:111], v[248:249]
	v_pk_mul_f32 v[108:109], v[108:109], v[100:101]
	v_pk_mul_f32 v[110:111], v[110:111], v[102:103]
	v_or_b32_e32 v112, 16, v164
	v_mad_i64_i32 v[112:113], s[10:11], v112, s86, v[160:161]
	v_lshl_add_u64 v[112:113], v[112:113], 0, v[162:163]
	v_pk_mul_f32 v[104:105], v[156:157], v[104:105] op_sel_hi:[0,1]
	v_pk_mul_f32 v[96:97], v[156:157], v[96:97] op_sel_hi:[0,1]
	v_pk_mul_f32 v[106:107], v[156:157], v[106:107] op_sel_hi:[0,1]
	v_pk_mul_f32 v[98:99], v[156:157], v[98:99] op_sel_hi:[0,1]
	v_pk_mul_f32 v[246:247], v[104:105], s[98:99]
	v_pk_mul_f32 v[248:249], v[106:107], s[98:99]
	v_exp_f32_e32 v246, v246
	v_exp_f32_e32 v247, v247
	v_exp_f32_e32 v248, v248
	v_exp_f32_e32 v249, v249
	v_pk_add_f32 v[246:247], v[246:247], s[100:101]
	v_pk_add_f32 v[248:249], v[248:249], s[100:101]
	v_rcp_f32_e32 v246, v246
	v_rcp_f32_e32 v247, v247
	v_rcp_f32_e32 v248, v248
	v_rcp_f32_e32 v249, v249
	v_pk_mul_f32 v[104:105], v[104:105], v[246:247]
	v_pk_mul_f32 v[106:107], v[106:107], v[248:249]
	v_pk_mul_f32 v[104:105], v[104:105], v[96:97]
	v_pk_mul_f32 v[106:107], v[106:107], v[98:99]
	v_cvt_pk_bf16_f32 v96, v108, v109
	v_cvt_pk_bf16_f32 v97, v110, v111
	v_cvt_pk_bf16_f32 v98, v104, v105
	v_cvt_pk_bf16_f32 v99, v106, v107
	global_store_dwordx4 v[112:113], v[96:99], off
	v_pk_mul_f32 v[92:93], v[154:155], v[92:93] op_sel_hi:[0,1]
	v_pk_mul_f32 v[84:85], v[154:155], v[84:85] op_sel_hi:[0,1]
	v_pk_mul_f32 v[94:95], v[154:155], v[94:95] op_sel_hi:[0,1]
	v_pk_mul_f32 v[86:87], v[154:155], v[86:87] op_sel_hi:[0,1]
	v_pk_mul_f32 v[246:247], v[92:93], s[98:99]
	v_pk_mul_f32 v[248:249], v[94:95], s[98:99]
	v_exp_f32_e32 v246, v246
	v_exp_f32_e32 v247, v247
	v_exp_f32_e32 v248, v248
	v_exp_f32_e32 v249, v249
	v_pk_add_f32 v[246:247], v[246:247], s[100:101]
	v_pk_add_f32 v[248:249], v[248:249], s[100:101]
	v_rcp_f32_e32 v246, v246
	v_rcp_f32_e32 v247, v247
	v_rcp_f32_e32 v248, v248
	v_rcp_f32_e32 v249, v249
	v_pk_mul_f32 v[92:93], v[92:93], v[246:247]
	v_pk_mul_f32 v[94:95], v[94:95], v[248:249]
	v_pk_mul_f32 v[92:93], v[92:93], v[84:85]
	v_pk_mul_f32 v[94:95], v[94:95], v[86:87]
	v_or_b32_e32 v96, 32, v164
	v_mad_i64_i32 v[96:97], s[10:11], v96, s86, v[160:161]
	v_lshl_add_u64 v[96:97], v[96:97], 0, v[162:163]
	v_pk_mul_f32 v[88:89], v[154:155], v[88:89] op_sel_hi:[0,1]
	v_pk_mul_f32 v[80:81], v[154:155], v[80:81] op_sel_hi:[0,1]
	v_pk_mul_f32 v[90:91], v[154:155], v[90:91] op_sel_hi:[0,1]
	v_pk_mul_f32 v[82:83], v[154:155], v[82:83] op_sel_hi:[0,1]
	v_pk_mul_f32 v[246:247], v[88:89], s[98:99]
	v_pk_mul_f32 v[248:249], v[90:91], s[98:99]
; __device__ __forceinline__ unsigned cvt_pk_bf16(float lo, float hi) { unsigned r; asm volatile("v_cvt_pk_bf16_f32 %0, %1, %2" : "=v"(r) : "v"(lo), "v"(hi)); return r; }
; __device__ __forceinline__ float silu_mul(float g, float u) {
;     const float e = __builtin_amdgcn_exp2f(g * -1.4426950408889634f);
;     return g * __builtin_amdgcn_rcpf(1.0f + e) * u;
; }
;     __device__ __forceinline__ void operator()(const f32x4 (&acc)[2][2][4][2], const Unit& u, int wr, int wc, int fr, int fq, const float (&rv)[8]) const {
;         const int row0 = u.pm * BM + wr * 64 + fr, col0 = u.pn * HALF + wc * 32 + 8 * fq;
; #pragma unroll
;         for (int ai = 0; ai < 2; ++ai)
; #pragma unroll
;             for (int m = 0; m < 4; ++m) {
;                 bf16_t* rowp = O + (size_t)(row0 + ai * HALF + m * 16) * ldc + col0;
;                 const float r = rv[ai * 4 + m];
;                 const f32x4 g0 = acc[ai][0][m][0] * r, g1 = acc[ai][0][m][1] * r, u0 = acc[ai][1][m][0] * r, u1 = acc[ai][1][m][1] * r;
;                 u32x4 w;
;                 w.x = cvt_pk_bf16(silu_mul(g0[0], u0[0]), silu_mul(g0[1], u0[1]));
;                 w.y = cvt_pk_bf16(silu_mul(g0[2], u0[2]), silu_mul(g0[3], u0[3]));
;                 w.z = cvt_pk_bf16(silu_mul(g1[0], u1[0]), silu_mul(g1[1], u1[1]));
;                 w.w = cvt_pk_bf16(silu_mul(g1[2], u1[2]), silu_mul(g1[3], u1[3]));
;                 *(u32x4*)rowp = w;
	v_exp_f32_e32 v246, v246
	v_exp_f32_e32 v247, v247
	v_exp_f32_e32 v248, v248
	v_exp_f32_e32 v249, v249
	v_pk_add_f32 v[246:247], v[246:247], s[100:101]
	v_pk_add_f32 v[248:249], v[248:249], s[100:101]
	v_rcp_f32_e32 v246, v246
	v_rcp_f32_e32 v247, v247
	v_rcp_f32_e32 v248, v248
	v_rcp_f32_e32 v249, v249
	v_pk_mul_f32 v[88:89], v[88:89], v[246:247]
	v_pk_mul_f32 v[90:91], v[90:91], v[248:249]
	v_pk_mul_f32 v[88:89], v[88:89], v[80:81]
	v_pk_mul_f32 v[90:91], v[90:91], v[82:83]
	v_cvt_pk_bf16_f32 v80, v92, v93
	v_cvt_pk_bf16_f32 v81, v94, v95
	v_cvt_pk_bf16_f32 v82, v88, v89
	v_cvt_pk_bf16_f32 v83, v90, v91
	global_store_dwordx4 v[96:97], v[80:83], off
	v_pk_mul_f32 v[76:77], v[152:153], v[76:77] op_sel_hi:[0,1]
	v_pk_mul_f32 v[68:69], v[152:153], v[68:69] op_sel_hi:[0,1]
	v_pk_mul_f32 v[78:79], v[152:153], v[78:79] op_sel_hi:[0,1]
	v_pk_mul_f32 v[70:71], v[152:153], v[70:71] op_sel_hi:[0,1]
	v_pk_mul_f32 v[246:247], v[76:77], s[98:99]
	v_pk_mul_f32 v[248:249], v[78:79], s[98:99]
	v_exp_f32_e32 v246, v246
	v_exp_f32_e32 v247, v247
	v_exp_f32_e32 v248, v248
	v_exp_f32_e32 v249, v249
	v_pk_add_f32 v[246:247], v[246:247], s[100:101]
	v_pk_add_f32 v[248:249], v[248:249], s[100:101]
	v_rcp_f32_e32 v246, v246
	v_rcp_f32_e32 v247, v247
	v_rcp_f32_e32 v248, v248
	v_rcp_f32_e32 v249, v249
	v_pk_mul_f32 v[76:77], v[76:77], v[246:247]
	v_pk_mul_f32 v[78:79], v[78:79], v[248:249]
	v_pk_mul_f32 v[76:77], v[76:77], v[68:69]
	v_pk_mul_f32 v[78:79], v[78:79], v[70:71]
	v_or_b32_e32 v80, 48, v164
	v_mad_i64_i32 v[80:81], s[10:11], v80, s86, v[160:161]
	v_lshl_add_u64 v[80:81], v[80:81], 0, v[162:163]
	v_pk_mul_f32 v[72:73], v[152:153], v[72:73] op_sel_hi:[0,1]
	v_pk_mul_f32 v[64:65], v[152:153], v[64:65] op_sel_hi:[0,1]
	v_pk_mul_f32 v[74:75], v[152:153], v[74:75] op_sel_hi:[0,1]
	v_pk_mul_f32 v[66:67], v[152:153], v[66:67] op_sel_hi:[0,1]
	v_pk_mul_f32 v[246:247], v[72:73], s[98:99]
	v_pk_mul_f32 v[248:249], v[74:75], s[98:99]
	v_exp_f32_e32 v246, v246
	v_exp_f32_e32 v247, v247
	v_exp_f32_e32 v248, v248
	v_exp_f32_e32 v249, v249
	v_pk_add_f32 v[246:247], v[246:247], s[100:101]
	v_pk_add_f32 v[248:249], v[248:249], s[100:101]
	v_rcp_f32_e32 v246, v246
	v_rcp_f32_e32 v247, v247
	v_rcp_f32_e32 v248, v248
	v_rcp_f32_e32 v249, v249
	v_pk_mul_f32 v[72:73], v[72:73], v[246:247]
	v_pk_mul_f32 v[74:75], v[74:75], v[248:249]
	v_pk_mul_f32 v[72:73], v[72:73], v[64:65]
	v_pk_mul_f32 v[74:75], v[74:75], v[66:67]
	v_cvt_pk_bf16_f32 v64, v76, v77
	v_cvt_pk_bf16_f32 v65, v78, v79
	v_cvt_pk_bf16_f32 v66, v72, v73
	v_cvt_pk_bf16_f32 v67, v74, v75
	global_store_dwordx4 v[80:81], v[64:67], off
	v_pk_mul_f32 v[60:61], v[150:151], v[60:61] op_sel_hi:[0,1]
	v_pk_mul_f32 v[52:53], v[150:151], v[52:53] op_sel_hi:[0,1]
	v_pk_mul_f32 v[62:63], v[150:151], v[62:63] op_sel_hi:[0,1]
	v_pk_mul_f32 v[54:55], v[150:151], v[54:55] op_sel_hi:[0,1]
	v_pk_mul_f32 v[246:247], v[60:61], s[98:99]
	v_pk_mul_f32 v[248:249], v[62:63], s[98:99]
	v_exp_f32_e32 v246, v246
	v_exp_f32_e32 v247, v247
	v_exp_f32_e32 v248, v248
	v_exp_f32_e32 v249, v249
	v_pk_add_f32 v[246:247], v[246:247], s[100:101]
	v_pk_add_f32 v[248:249], v[248:249], s[100:101]
	v_rcp_f32_e32 v246, v246
	v_rcp_f32_e32 v247, v247
	v_rcp_f32_e32 v248, v248
	v_rcp_f32_e32 v249, v249
	v_pk_mul_f32 v[60:61], v[60:61], v[246:247]
	v_pk_mul_f32 v[62:63], v[62:63], v[248:249]
	v_pk_mul_f32 v[60:61], v[60:61], v[52:53]
	v_pk_mul_f32 v[62:63], v[62:63], v[54:55]
	v_add_u32_e32 v64, 0x80, v164
	v_mad_i64_i32 v[64:65], s[10:11], v64, s86, v[160:161]
	v_lshl_add_u64 v[64:65], v[64:65], 0, v[162:163]
	v_pk_mul_f32 v[56:57], v[150:151], v[56:57] op_sel_hi:[0,1]
	v_pk_mul_f32 v[48:49], v[150:151], v[48:49] op_sel_hi:[0,1]
	v_pk_mul_f32 v[58:59], v[150:151], v[58:59] op_sel_hi:[0,1]
	v_pk_mul_f32 v[50:51], v[150:151], v[50:51] op_sel_hi:[0,1]
	v_pk_mul_f32 v[246:247], v[56:57], s[98:99]
	v_pk_mul_f32 v[248:249], v[58:59], s[98:99]
	v_exp_f32_e32 v246, v246
	v_exp_f32_e32 v247, v247
	v_exp_f32_e32 v248, v248
	v_exp_f32_e32 v249, v249
	v_pk_add_f32 v[246:247], v[246:247], s[100:101]
	v_pk_add_f32 v[248:249], v[248:249], s[100:101]
	v_rcp_f32_e32 v246, v246
	v_rcp_f32_e32 v247, v247
	v_rcp_f32_e32 v248, v248
	v_rcp_f32_e32 v249, v249
	v_pk_mul_f32 v[56:57], v[56:57], v[246:247]
	v_pk_mul_f32 v[58:59], v[58:59], v[248:249]
	v_pk_mul_f32 v[56:57], v[56:57], v[48:49]
	v_pk_mul_f32 v[58:59], v[58:59], v[50:51]
	v_cvt_pk_bf16_f32 v48, v60, v61
	v_cvt_pk_bf16_f32 v49, v62, v63
	v_cvt_pk_bf16_f32 v50, v56, v57
	v_cvt_pk_bf16_f32 v51, v58, v59
	global_store_dwordx4 v[64:65], v[48:51], off
	v_pk_mul_f32 v[44:45], v[148:149], v[44:45] op_sel_hi:[0,1]
	v_pk_mul_f32 v[36:37], v[148:149], v[36:37] op_sel_hi:[0,1]
	v_pk_mul_f32 v[46:47], v[148:149], v[46:47] op_sel_hi:[0,1]
	v_pk_mul_f32 v[38:39], v[148:149], v[38:39] op_sel_hi:[0,1]
	v_pk_mul_f32 v[246:247], v[44:45], s[98:99]
	v_pk_mul_f32 v[248:249], v[46:47], s[98:99]
	v_exp_f32_e32 v246, v246
	v_exp_f32_e32 v247, v247
	v_exp_f32_e32 v248, v248
	v_exp_f32_e32 v249, v249
	v_pk_add_f32 v[246:247], v[246:247], s[100:101]
	v_pk_add_f32 v[248:249], v[248:249], s[100:101]
	v_rcp_f32_e32 v246, v246
	v_rcp_f32_e32 v247, v247
	v_rcp_f32_e32 v248, v248
	v_rcp_f32_e32 v249, v249
	v_pk_mul_f32 v[44:45], v[44:45], v[246:247]
	v_pk_mul_f32 v[46:47], v[46:47], v[248:249]
	v_pk_mul_f32 v[44:45], v[44:45], v[36:37]
	v_pk_mul_f32 v[46:47], v[46:47], v[38:39]
	v_add_u32_e32 v48, 0x90, v164
	v_mad_i64_i32 v[48:49], s[10:11], v48, s86, v[160:161]
	v_lshl_add_u64 v[48:49], v[48:49], 0, v[162:163]
; __device__ __forceinline__ unsigned cvt_pk_bf16(float lo, float hi) { unsigned r; asm volatile("v_cvt_pk_bf16_f32 %0, %1, %2" : "=v"(r) : "v"(lo), "v"(hi)); return r; }
;     __device__ __forceinline__ void pre(const Unit& u, int wr, int fr, float (&rv)[8]) const {
; #pragma unroll
;         for (int i = 0; i < 8; ++i) rv[i] = rs[u.pm * BM + wr * 64 + fr + (i >> 2) * HALF + (i & 3) * 16];
;     }
;     __device__ __forceinline__ void operator()(const f32x4 (&acc)[2][2][4][2], const Unit& u, int wr, int wc, int fr, int fq, const float (&rv)[8]) const {
;     ...
;         for (int ai = 0; ai < 2; ++ai)
; #pragma unroll
;             for (int m = 0; m < 4; ++m) {
;                 bf16_t* rowp = O + (size_t)(row0 + ai * HALF + m * 16) * ldc + col0;
;                 const float r = rv[ai * 4 + m];
;                 const f32x4 g0 = acc[ai][0][m][0] * r, g1 = acc[ai][0][m][1] * r, u0 = acc[ai][1][m][0] * r, u1 = acc[ai][1][m][1] * r;
;                 u32x4 w;
;                 w.x = cvt_pk_bf16(silu_mul(g0[0], u0[0]), silu_mul(g0[1], u0[1]));
;                 w.y = cvt_pk_bf16(silu_mul(g0[2], u0[2]), silu_mul(g0[3], u0[3]));
;                 w.z = cvt_pk_bf16(silu_mul(g1[0], u1[0]), silu_mul(g1[1], u1[1]));
;                 w.w = cvt_pk_bf16(silu_mul(g1[2], u1[2]), silu_mul(g1[3], u1[3]));
;                 *(u32x4*)rowp = w;
;             }
	v_pk_mul_f32 v[40:41], v[148:149], v[40:41] op_sel_hi:[0,1]
	v_pk_mul_f32 v[32:33], v[148:149], v[32:33] op_sel_hi:[0,1]
	v_pk_mul_f32 v[42:43], v[148:149], v[42:43] op_sel_hi:[0,1]
	v_pk_mul_f32 v[34:35], v[148:149], v[34:35] op_sel_hi:[0,1]
	v_pk_mul_f32 v[246:247], v[40:41], s[98:99]
	v_pk_mul_f32 v[248:249], v[42:43], s[98:99]
	v_exp_f32_e32 v246, v246
	v_exp_f32_e32 v247, v247
	v_exp_f32_e32 v248, v248
	v_exp_f32_e32 v249, v249
	v_pk_add_f32 v[246:247], v[246:247], s[100:101]
	v_pk_add_f32 v[248:249], v[248:249], s[100:101]
	v_rcp_f32_e32 v246, v246
	v_rcp_f32_e32 v247, v247
	v_rcp_f32_e32 v248, v248
	v_rcp_f32_e32 v249, v249
	v_pk_mul_f32 v[40:41], v[40:41], v[246:247]
	v_pk_mul_f32 v[42:43], v[42:43], v[248:249]
	v_pk_mul_f32 v[40:41], v[40:41], v[32:33]
	v_pk_mul_f32 v[42:43], v[42:43], v[34:35]
	v_cvt_pk_bf16_f32 v32, v44, v45
	v_cvt_pk_bf16_f32 v33, v46, v47
	v_cvt_pk_bf16_f32 v34, v40, v41
	v_cvt_pk_bf16_f32 v35, v42, v43
	global_store_dwordx4 v[48:49], v[32:35], off
	v_pk_mul_f32 v[28:29], v[146:147], v[28:29] op_sel_hi:[0,1]
	v_pk_mul_f32 v[20:21], v[146:147], v[20:21] op_sel_hi:[0,1]
	v_pk_mul_f32 v[30:31], v[146:147], v[30:31] op_sel_hi:[0,1]
	v_pk_mul_f32 v[22:23], v[146:147], v[22:23] op_sel_hi:[0,1]
	v_pk_mul_f32 v[246:247], v[28:29], s[98:99]
	v_pk_mul_f32 v[248:249], v[30:31], s[98:99]
	v_exp_f32_e32 v246, v246
	v_exp_f32_e32 v247, v247
	v_exp_f32_e32 v248, v248
	v_exp_f32_e32 v249, v249
	v_pk_add_f32 v[246:247], v[246:247], s[100:101]
	v_pk_add_f32 v[248:249], v[248:249], s[100:101]
	v_rcp_f32_e32 v246, v246
	v_rcp_f32_e32 v247, v247
	v_rcp_f32_e32 v248, v248
	v_rcp_f32_e32 v249, v249
	v_pk_mul_f32 v[28:29], v[28:29], v[246:247]
	v_pk_mul_f32 v[30:31], v[30:31], v[248:249]
	v_pk_mul_f32 v[28:29], v[28:29], v[20:21]
	v_pk_mul_f32 v[30:31], v[30:31], v[22:23]
	v_add_u32_e32 v32, 0xa0, v164
	v_mad_i64_i32 v[32:33], s[10:11], v32, s86, v[160:161]
	v_lshl_add_u64 v[32:33], v[32:33], 0, v[162:163]
	v_pk_mul_f32 v[24:25], v[146:147], v[24:25] op_sel_hi:[0,1]
	v_pk_mul_f32 v[16:17], v[146:147], v[16:17] op_sel_hi:[0,1]
	v_pk_mul_f32 v[26:27], v[146:147], v[26:27] op_sel_hi:[0,1]
	v_pk_mul_f32 v[18:19], v[146:147], v[18:19] op_sel_hi:[0,1]
	v_pk_mul_f32 v[246:247], v[24:25], s[98:99]
	v_pk_mul_f32 v[248:249], v[26:27], s[98:99]
	v_exp_f32_e32 v246, v246
	v_exp_f32_e32 v247, v247
	v_exp_f32_e32 v248, v248
	v_exp_f32_e32 v249, v249
	v_pk_add_f32 v[246:247], v[246:247], s[100:101]
	v_pk_add_f32 v[248:249], v[248:249], s[100:101]
	v_rcp_f32_e32 v246, v246
	v_rcp_f32_e32 v247, v247
	v_rcp_f32_e32 v248, v248
	v_rcp_f32_e32 v249, v249
	v_pk_mul_f32 v[24:25], v[24:25], v[246:247]
	v_pk_mul_f32 v[26:27], v[26:27], v[248:249]
	v_pk_mul_f32 v[24:25], v[24:25], v[16:17]
	v_pk_mul_f32 v[26:27], v[26:27], v[18:19]
	v_cvt_pk_bf16_f32 v16, v28, v29
	v_cvt_pk_bf16_f32 v17, v30, v31
	v_cvt_pk_bf16_f32 v18, v24, v25
	v_cvt_pk_bf16_f32 v19, v26, v27
	global_store_dwordx4 v[32:33], v[16:19], off
	v_pk_mul_f32 v[12:13], v[136:137], v[12:13] op_sel_hi:[0,1]
	v_pk_mul_f32 v[4:5], v[136:137], v[4:5] op_sel_hi:[0,1]
	v_pk_mul_f32 v[14:15], v[136:137], v[14:15] op_sel_hi:[0,1]
	v_pk_mul_f32 v[6:7], v[136:137], v[6:7] op_sel_hi:[0,1]
	v_pk_mul_f32 v[246:247], v[12:13], s[98:99]
	v_pk_mul_f32 v[248:249], v[14:15], s[98:99]
	v_exp_f32_e32 v246, v246
	v_exp_f32_e32 v247, v247
	v_exp_f32_e32 v248, v248
	v_exp_f32_e32 v249, v249
	v_pk_add_f32 v[246:247], v[246:247], s[100:101]
	v_pk_add_f32 v[248:249], v[248:249], s[100:101]
	v_rcp_f32_e32 v246, v246
	v_rcp_f32_e32 v247, v247
	v_rcp_f32_e32 v248, v248
	v_rcp_f32_e32 v249, v249
	v_pk_mul_f32 v[12:13], v[12:13], v[246:247]
	v_pk_mul_f32 v[14:15], v[14:15], v[248:249]
	v_pk_mul_f32 v[12:13], v[12:13], v[4:5]
	v_pk_mul_f32 v[14:15], v[14:15], v[6:7]
	v_add_u32_e32 v16, 0xb0, v164
	v_mad_i64_i32 v[16:17], s[10:11], v16, s86, v[160:161]
	v_lshl_add_u64 v[16:17], v[16:17], 0, v[162:163]
	s_andn2_b64 vcc, exec, s[0:1]
	s_mov_b64 s[0:1], -1
	v_pk_mul_f32 v[8:9], v[136:137], v[8:9] op_sel_hi:[0,1]
	v_pk_mul_f32 v[0:1], v[136:137], v[0:1] op_sel_hi:[0,1]
	v_pk_mul_f32 v[10:11], v[136:137], v[10:11] op_sel_hi:[0,1]
	v_pk_mul_f32 v[2:3], v[136:137], v[2:3] op_sel_hi:[0,1]
	v_pk_mul_f32 v[246:247], v[8:9], s[98:99]
	v_pk_mul_f32 v[248:249], v[10:11], s[98:99]
	v_exp_f32_e32 v246, v246
	v_exp_f32_e32 v247, v247
	v_exp_f32_e32 v248, v248
	v_exp_f32_e32 v249, v249
	v_pk_add_f32 v[246:247], v[246:247], s[100:101]
	v_pk_add_f32 v[248:249], v[248:249], s[100:101]
	v_rcp_f32_e32 v246, v246
	v_rcp_f32_e32 v247, v247
	v_rcp_f32_e32 v248, v248
	v_rcp_f32_e32 v249, v249
	v_pk_mul_f32 v[8:9], v[8:9], v[246:247]
	v_pk_mul_f32 v[10:11], v[10:11], v[248:249]
	v_pk_mul_f32 v[8:9], v[8:9], v[0:1]
	v_pk_mul_f32 v[10:11], v[10:11], v[2:3]
	v_cvt_pk_bf16_f32 v0, v12, v13
	v_cvt_pk_bf16_f32 v1, v14, v15
	v_cvt_pk_bf16_f32 v2, v8, v9
	v_cvt_pk_bf16_f32 v3, v10, v11
	global_store_dwordx4 v[16:17], v[0:3], off
	s_cbranch_vccnz .LBB0_98
	s_nop 0
	v_lshl_add_u32 v0, s54, 8, v137
	v_ashrrev_i32_e32 v1, 31, v0
	v_lshl_add_u64 v[0:1], v[0:1], 2, s[16:17]
	global_load_dword v158, v[0:1], off
	global_load_dword v156, v[0:1], off offset:64
	global_load_dword v154, v[0:1], off offset:128
	global_load_dword v152, v[0:1], off offset:192
	global_load_dword v150, v[0:1], off offset:512
	global_load_dword v148, v[0:1], off offset:576
	global_load_dword v146, v[0:1], off offset:640
	global_load_dword v136, v[0:1], off offset:704
	s_andn2_b64 vcc, exec, s[6:7]
	s_cbranch_vccnz .LBB0_97
	s_barrier
	s_branch .LBB0_97

; __device__ __forceinline__ unsigned cvt_pk_bf16(float lo, float hi) { unsigned r; asm volatile("v_cvt_pk_bf16_f32 %0, %1, %2" : "=v"(r) : "v"(lo), "v"(hi)); return r; }
; __device__ __forceinline__ float silu_mul(float g, float u) {
;     const float e = __builtin_amdgcn_exp2f(g * -1.4426950408889634f);
;     return g * __builtin_amdgcn_rcpf(1.0f + e) * u;
; }
;     __device__ __forceinline__ void operator()(const f32x4 (&acc)[2][2][4][2], const Unit& u, int wr, int wc, int fr, int fq, const float (&rv)[8]) const {
;     ...
;         for (int ai = 0; ai < 2; ++ai)
; #pragma unroll
;             for (int m = 0; m < 4; ++m) {
;                 bf16_t* rowp = O + (size_t)(row0 + ai * HALF + m * 16) * ldc + col0;
;                 const float r = rv[ai * 4 + m];
;                 const f32x4 g0 = acc[ai][0][m][0] * r, g1 = acc[ai][0][m][1] * r, u0 = acc[ai][1][m][0] * r, u1 = acc[ai][1][m][1] * r;
;                 u32x4 w;
;                 w.x = cvt_pk_bf16(silu_mul(g0[0], u0[0]), silu_mul(g0[1], u0[1]));
;                 w.y = cvt_pk_bf16(silu_mul(g0[2], u0[2]), silu_mul(g0[3], u0[3]));
;                 w.z = cvt_pk_bf16(silu_mul(g1[0], u1[0]), silu_mul(g1[1], u1[1]));
;                 w.w = cvt_pk_bf16(silu_mul(g1[2], u1[2]), silu_mul(g1[3], u1[3]));
;                 *(u32x4*)rowp = w;
;             }
.LBB0_703:
	s_waitcnt vmcnt(0)
	s_mov_b32 s98, 0xbfb8aa3b
	s_mov_b32 s99, 0xbfb8aa3b
	s_mov_b32 s100, 1.0
	s_mov_b32 s101, 1.0
	s_nop 7
	s_nop 7
	v_pk_mul_f32 v[124:125], v[162:163], v[124:125] op_sel_hi:[0,1]
	v_pk_mul_f32 v[116:117], v[162:163], v[116:117] op_sel_hi:[0,1]
	v_pk_mul_f32 v[126:127], v[162:163], v[126:127] op_sel_hi:[0,1]
	v_pk_mul_f32 v[118:119], v[162:163], v[118:119] op_sel_hi:[0,1]
	v_pk_mul_f32 v[246:247], v[124:125], s[98:99]
	v_pk_mul_f32 v[248:249], v[126:127], s[98:99]
	v_exp_f32_e32 v246, v246
	v_exp_f32_e32 v247, v247
	v_exp_f32_e32 v248, v248
	v_exp_f32_e32 v249, v249
	v_pk_add_f32 v[246:247], v[246:247], s[100:101]
	v_pk_add_f32 v[248:249], v[248:249], s[100:101]
	v_rcp_f32_e32 v246, v246
	v_rcp_f32_e32 v247, v247
	v_rcp_f32_e32 v248, v248
	v_rcp_f32_e32 v249, v249
	v_pk_mul_f32 v[124:125], v[124:125], v[246:247]
	v_pk_mul_f32 v[126:127], v[126:127], v[248:249]
	v_pk_mul_f32 v[124:125], v[124:125], v[116:117]
	v_pk_mul_f32 v[126:127], v[126:127], v[118:119]
	v_lshl_or_b32 v166, s64, 7, v153
	v_lshl_add_u32 v161, s42, 8, v137
	v_ashrrev_i32_e32 v167, 31, v166
	v_mov_b64_e32 v[164:165], s[14:15]
	v_mad_i64_i32 v[168:169], s[10:11], v161, s61, v[164:165]
	v_lshlrev_b64 v[166:167], 1, v[166:167]
	v_lshl_add_u64 v[168:169], v[168:169], 0, v[166:167]
	v_pk_mul_f32 v[120:121], v[162:163], v[120:121] op_sel_hi:[0,1]
	v_pk_mul_f32 v[112:113], v[162:163], v[112:113] op_sel_hi:[0,1]
	v_pk_mul_f32 v[122:123], v[162:163], v[122:123] op_sel_hi:[0,1]
	v_pk_mul_f32 v[114:115], v[162:163], v[114:115] op_sel_hi:[0,1]
	v_pk_mul_f32 v[246:247], v[120:121], s[98:99]
	v_pk_mul_f32 v[248:249], v[122:123], s[98:99]
	v_exp_f32_e32 v246, v246
	v_exp_f32_e32 v247, v247
	v_exp_f32_e32 v248, v248
	v_exp_f32_e32 v249, v249
	v_pk_add_f32 v[246:247], v[246:247], s[100:101]
	v_pk_add_f32 v[248:249], v[248:249], s[100:101]
	v_rcp_f32_e32 v246, v246
	v_rcp_f32_e32 v247, v247
	v_rcp_f32_e32 v248, v248
	v_rcp_f32_e32 v249, v249
	v_pk_mul_f32 v[120:121], v[120:121], v[246:247]
	v_pk_mul_f32 v[122:123], v[122:123], v[248:249]
	v_pk_mul_f32 v[120:121], v[120:121], v[112:113]
	v_pk_mul_f32 v[122:123], v[122:123], v[114:115]
	v_cvt_pk_bf16_f32 v112, v124, v125
	v_cvt_pk_bf16_f32 v113, v126, v127
	v_cvt_pk_bf16_f32 v114, v120, v121
	v_cvt_pk_bf16_f32 v115, v122, v123
	global_store_dwordx4 v[168:169], v[112:115], off
	v_pk_mul_f32 v[108:109], v[160:161], v[108:109] op_sel_hi:[0,1]
	v_pk_mul_f32 v[100:101], v[160:161], v[100:101] op_sel_hi:[0,1]
	v_pk_mul_f32 v[110:111], v[160:161], v[110:111] op_sel_hi:[0,1]
	v_pk_mul_f32 v[102:103], v[160:161], v[102:103] op_sel_hi:[0,1]
	v_pk_mul_f32 v[246:247], v[108:109], s[98:99]
	v_pk_mul_f32 v[248:249], v[110:111], s[98:99]
	v_exp_f32_e32 v246, v246
	v_exp_f32_e32 v247, v247
	v_exp_f32_e32 v248, v248
	v_exp_f32_e32 v249, v249
	v_pk_add_f32 v[246:247], v[246:247], s[100:101]
	v_pk_add_f32 v[248:249], v[248:249], s[100:101]
	v_rcp_f32_e32 v246, v246
	v_rcp_f32_e32 v247, v247
	v_rcp_f32_e32 v248, v248
	v_rcp_f32_e32 v249, v249
	v_pk_mul_f32 v[108:109], v[108:109], v[246:247]
	v_pk_mul_f32 v[110:111], v[110:111], v[248:249]
	v_pk_mul_f32 v[108:109], v[108:109], v[100:101]
	v_pk_mul_f32 v[110:111], v[110:111], v[102:103]
	v_or_b32_e32 v112, 16, v161
	v_mad_i64_i32 v[112:113], s[10:11], v112, s61, v[164:165]
	v_lshl_add_u64 v[112:113], v[112:113], 0, v[166:167]
	v_pk_mul_f32 v[104:105], v[160:161], v[104:105] op_sel_hi:[0,1]
	v_pk_mul_f32 v[96:97], v[160:161], v[96:97] op_sel_hi:[0,1]
	v_pk_mul_f32 v[106:107], v[160:161], v[106:107] op_sel_hi:[0,1]
	v_pk_mul_f32 v[98:99], v[160:161], v[98:99] op_sel_hi:[0,1]
	v_pk_mul_f32 v[246:247], v[104:105], s[98:99]
	v_pk_mul_f32 v[248:249], v[106:107], s[98:99]
	v_exp_f32_e32 v246, v246
	v_exp_f32_e32 v247, v247
	v_exp_f32_e32 v248, v248
	v_exp_f32_e32 v249, v249
	v_pk_add_f32 v[246:247], v[246:247], s[100:101]
	v_pk_add_f32 v[248:249], v[248:249], s[100:101]
	v_rcp_f32_e32 v246, v246
	v_rcp_f32_e32 v247, v247
	v_rcp_f32_e32 v248, v248
	v_rcp_f32_e32 v249, v249
	v_pk_mul_f32 v[104:105], v[104:105], v[246:247]
	v_pk_mul_f32 v[106:107], v[106:107], v[248:249]
	v_pk_mul_f32 v[104:105], v[104:105], v[96:97]
	v_pk_mul_f32 v[106:107], v[106:107], v[98:99]
	v_cvt_pk_bf16_f32 v96, v108, v109
	v_cvt_pk_bf16_f32 v97, v110, v111
	v_cvt_pk_bf16_f32 v98, v104, v105
	v_cvt_pk_bf16_f32 v99, v106, v107
	global_store_dwordx4 v[112:113], v[96:99], off
	v_pk_mul_f32 v[92:93], v[158:159], v[92:93] op_sel_hi:[0,1]
	v_pk_mul_f32 v[84:85], v[158:159], v[84:85] op_sel_hi:[0,1]
	v_pk_mul_f32 v[94:95], v[158:159], v[94:95] op_sel_hi:[0,1]
	v_pk_mul_f32 v[86:87], v[158:159], v[86:87] op_sel_hi:[0,1]
	v_pk_mul_f32 v[246:247], v[92:93], s[98:99]
	v_pk_mul_f32 v[248:249], v[94:95], s[98:99]
	v_exp_f32_e32 v246, v246
	v_exp_f32_e32 v247, v247
	v_exp_f32_e32 v248, v248
	v_exp_f32_e32 v249, v249
	v_pk_add_f32 v[246:247], v[246:247], s[100:101]
	v_pk_add_f32 v[248:249], v[248:249], s[100:101]
	v_rcp_f32_e32 v246, v246
	v_rcp_f32_e32 v247, v247
	v_rcp_f32_e32 v248, v248
	v_rcp_f32_e32 v249, v249
	v_pk_mul_f32 v[92:93], v[92:93], v[246:247]
	v_pk_mul_f32 v[94:95], v[94:95], v[248:249]
	v_pk_mul_f32 v[92:93], v[92:93], v[84:85]
	v_pk_mul_f32 v[94:95], v[94:95], v[86:87]
	v_or_b32_e32 v96, 32, v161
	v_mad_i64_i32 v[96:97], s[10:11], v96, s61, v[164:165]
	v_lshl_add_u64 v[96:97], v[96:97], 0, v[166:167]
	v_pk_mul_f32 v[88:89], v[158:159], v[88:89] op_sel_hi:[0,1]
	v_pk_mul_f32 v[80:81], v[158:159], v[80:81] op_sel_hi:[0,1]
	v_pk_mul_f32 v[90:91], v[158:159], v[90:91] op_sel_hi:[0,1]
	v_pk_mul_f32 v[82:83], v[158:159], v[82:83] op_sel_hi:[0,1]
	v_pk_mul_f32 v[246:247], v[88:89], s[98:99]
	v_pk_mul_f32 v[248:249], v[90:91], s[98:99]
; __device__ __forceinline__ unsigned cvt_pk_bf16(float lo, float hi) { unsigned r; asm volatile("v_cvt_pk_bf16_f32 %0, %1, %2" : "=v"(r) : "v"(lo), "v"(hi)); return r; }
;     __device__ __forceinline__ void operator()(const f32x4 (&acc)[2][2][4][2], const Unit& u, int wr, int wc, int fr, int fq, const float (&rv)[8]) const {
;     ...
;         for (int ai = 0; ai < 2; ++ai)
; #pragma unroll
;             for (int m = 0; m < 4; ++m) {
;                 bf16_t* rowp = O + (size_t)(row0 + ai * HALF + m * 16) * ldc + col0;
;                 const float r = rv[ai * 4 + m];
;                 const f32x4 g0 = acc[ai][0][m][0] * r, g1 = acc[ai][0][m][1] * r, u0 = acc[ai][1][m][0] * r, u1 = acc[ai][1][m][1] * r;
;                 u32x4 w;
;                 w.x = cvt_pk_bf16(silu_mul(g0[0], u0[0]), silu_mul(g0[1], u0[1]));
;                 w.y = cvt_pk_bf16(silu_mul(g0[2], u0[2]), silu_mul(g0[3], u0[3]));
;                 w.z = cvt_pk_bf16(silu_mul(g1[0], u1[0]), silu_mul(g1[1], u1[1]));
;                 w.w = cvt_pk_bf16(silu_mul(g1[2], u1[2]), silu_mul(g1[3], u1[3]));
;                 *(u32x4*)rowp = w;
;             }
	v_exp_f32_e32 v246, v246
	v_exp_f32_e32 v247, v247
	v_exp_f32_e32 v248, v248
	v_exp_f32_e32 v249, v249
	v_pk_add_f32 v[246:247], v[246:247], s[100:101]
	v_pk_add_f32 v[248:249], v[248:249], s[100:101]
	v_rcp_f32_e32 v246, v246
	v_rcp_f32_e32 v247, v247
	v_rcp_f32_e32 v248, v248
	v_rcp_f32_e32 v249, v249
	v_pk_mul_f32 v[88:89], v[88:89], v[246:247]
	v_pk_mul_f32 v[90:91], v[90:91], v[248:249]
	v_pk_mul_f32 v[88:89], v[88:89], v[80:81]
	v_pk_mul_f32 v[90:91], v[90:91], v[82:83]
	v_cvt_pk_bf16_f32 v80, v92, v93
	v_cvt_pk_bf16_f32 v81, v94, v95
	v_cvt_pk_bf16_f32 v82, v88, v89
	v_cvt_pk_bf16_f32 v83, v90, v91
	global_store_dwordx4 v[96:97], v[80:83], off
	v_pk_mul_f32 v[76:77], v[156:157], v[76:77] op_sel_hi:[0,1]
	v_pk_mul_f32 v[68:69], v[156:157], v[68:69] op_sel_hi:[0,1]
	v_pk_mul_f32 v[78:79], v[156:157], v[78:79] op_sel_hi:[0,1]
	v_pk_mul_f32 v[70:71], v[156:157], v[70:71] op_sel_hi:[0,1]
	v_pk_mul_f32 v[246:247], v[76:77], s[98:99]
	v_pk_mul_f32 v[248:249], v[78:79], s[98:99]
	v_exp_f32_e32 v246, v246
	v_exp_f32_e32 v247, v247
	v_exp_f32_e32 v248, v248
	v_exp_f32_e32 v249, v249
	v_pk_add_f32 v[246:247], v[246:247], s[100:101]
	v_pk_add_f32 v[248:249], v[248:249], s[100:101]
	v_rcp_f32_e32 v246, v246
	v_rcp_f32_e32 v247, v247
	v_rcp_f32_e32 v248, v248
	v_rcp_f32_e32 v249, v249
	v_pk_mul_f32 v[76:77], v[76:77], v[246:247]
	v_pk_mul_f32 v[78:79], v[78:79], v[248:249]
	v_pk_mul_f32 v[76:77], v[76:77], v[68:69]
	v_pk_mul_f32 v[78:79], v[78:79], v[70:71]
	v_or_b32_e32 v80, 48, v161
	v_mad_i64_i32 v[80:81], s[10:11], v80, s61, v[164:165]
	v_lshl_add_u64 v[80:81], v[80:81], 0, v[166:167]
	v_pk_mul_f32 v[72:73], v[156:157], v[72:73] op_sel_hi:[0,1]
	v_pk_mul_f32 v[64:65], v[156:157], v[64:65] op_sel_hi:[0,1]
	v_pk_mul_f32 v[74:75], v[156:157], v[74:75] op_sel_hi:[0,1]
	v_pk_mul_f32 v[66:67], v[156:157], v[66:67] op_sel_hi:[0,1]
	v_pk_mul_f32 v[246:247], v[72:73], s[98:99]
	v_pk_mul_f32 v[248:249], v[74:75], s[98:99]
	v_exp_f32_e32 v246, v246
	v_exp_f32_e32 v247, v247
	v_exp_f32_e32 v248, v248
	v_exp_f32_e32 v249, v249
	v_pk_add_f32 v[246:247], v[246:247], s[100:101]
	v_pk_add_f32 v[248:249], v[248:249], s[100:101]
	v_rcp_f32_e32 v246, v246
	v_rcp_f32_e32 v247, v247
	v_rcp_f32_e32 v248, v248
	v_rcp_f32_e32 v249, v249
	v_pk_mul_f32 v[72:73], v[72:73], v[246:247]
	v_pk_mul_f32 v[74:75], v[74:75], v[248:249]
	v_pk_mul_f32 v[72:73], v[72:73], v[64:65]
	v_pk_mul_f32 v[74:75], v[74:75], v[66:67]
	v_cvt_pk_bf16_f32 v64, v76, v77
	v_cvt_pk_bf16_f32 v65, v78, v79
	v_cvt_pk_bf16_f32 v66, v72, v73
	v_cvt_pk_bf16_f32 v67, v74, v75
	global_store_dwordx4 v[80:81], v[64:67], off
	v_pk_mul_f32 v[60:61], v[154:155], v[60:61] op_sel_hi:[0,1]
	v_pk_mul_f32 v[52:53], v[154:155], v[52:53] op_sel_hi:[0,1]
	v_pk_mul_f32 v[62:63], v[154:155], v[62:63] op_sel_hi:[0,1]
	v_pk_mul_f32 v[54:55], v[154:155], v[54:55] op_sel_hi:[0,1]
	v_pk_mul_f32 v[246:247], v[60:61], s[98:99]
	v_pk_mul_f32 v[248:249], v[62:63], s[98:99]
	v_exp_f32_e32 v246, v246
	v_exp_f32_e32 v247, v247
	v_exp_f32_e32 v248, v248
	v_exp_f32_e32 v249, v249
	v_pk_add_f32 v[246:247], v[246:247], s[100:101]
	v_pk_add_f32 v[248:249], v[248:249], s[100:101]
	v_rcp_f32_e32 v246, v246
	v_rcp_f32_e32 v247, v247
	v_rcp_f32_e32 v248, v248
	v_rcp_f32_e32 v249, v249
	v_pk_mul_f32 v[60:61], v[60:61], v[246:247]
	v_pk_mul_f32 v[62:63], v[62:63], v[248:249]
	v_pk_mul_f32 v[60:61], v[60:61], v[52:53]
	v_pk_mul_f32 v[62:63], v[62:63], v[54:55]
	v_add_u32_e32 v64, 0x80, v161
	v_mad_i64_i32 v[64:65], s[10:11], v64, s61, v[164:165]
	v_lshl_add_u64 v[64:65], v[64:65], 0, v[166:167]
	v_pk_mul_f32 v[56:57], v[154:155], v[56:57] op_sel_hi:[0,1]
	v_pk_mul_f32 v[48:49], v[154:155], v[48:49] op_sel_hi:[0,1]
	v_pk_mul_f32 v[58:59], v[154:155], v[58:59] op_sel_hi:[0,1]
	v_pk_mul_f32 v[50:51], v[154:155], v[50:51] op_sel_hi:[0,1]
	v_pk_mul_f32 v[246:247], v[56:57], s[98:99]
	v_pk_mul_f32 v[248:249], v[58:59], s[98:99]
	v_exp_f32_e32 v246, v246
	v_exp_f32_e32 v247, v247
	v_exp_f32_e32 v248, v248
	v_exp_f32_e32 v249, v249
	v_pk_add_f32 v[246:247], v[246:247], s[100:101]
	v_pk_add_f32 v[248:249], v[248:249], s[100:101]
	v_rcp_f32_e32 v246, v246
	v_rcp_f32_e32 v247, v247
	v_rcp_f32_e32 v248, v248
	v_rcp_f32_e32 v249, v249
	v_pk_mul_f32 v[56:57], v[56:57], v[246:247]
	v_pk_mul_f32 v[58:59], v[58:59], v[248:249]
	v_pk_mul_f32 v[56:57], v[56:57], v[48:49]
	v_pk_mul_f32 v[58:59], v[58:59], v[50:51]
	v_cvt_pk_bf16_f32 v48, v60, v61
	v_cvt_pk_bf16_f32 v49, v62, v63
	v_cvt_pk_bf16_f32 v50, v56, v57
	v_cvt_pk_bf16_f32 v51, v58, v59
	global_store_dwordx4 v[64:65], v[48:51], off
	v_pk_mul_f32 v[44:45], v[152:153], v[44:45] op_sel_hi:[0,1]
	v_pk_mul_f32 v[36:37], v[152:153], v[36:37] op_sel_hi:[0,1]
	v_pk_mul_f32 v[46:47], v[152:153], v[46:47] op_sel_hi:[0,1]
	v_pk_mul_f32 v[38:39], v[152:153], v[38:39] op_sel_hi:[0,1]
	v_pk_mul_f32 v[246:247], v[44:45], s[98:99]
	v_pk_mul_f32 v[248:249], v[46:47], s[98:99]
	v_exp_f32_e32 v246, v246
	v_exp_f32_e32 v247, v247
	v_exp_f32_e32 v248, v248
	v_exp_f32_e32 v249, v249
	v_pk_add_f32 v[246:247], v[246:247], s[100:101]
	v_pk_add_f32 v[248:249], v[248:249], s[100:101]
	v_rcp_f32_e32 v246, v246
	v_rcp_f32_e32 v247, v247
	v_rcp_f32_e32 v248, v248
	v_rcp_f32_e32 v249, v249
	v_pk_mul_f32 v[44:45], v[44:45], v[246:247]
	v_pk_mul_f32 v[46:47], v[46:47], v[248:249]
	v_pk_mul_f32 v[44:45], v[44:45], v[36:37]
	v_pk_mul_f32 v[46:47], v[46:47], v[38:39]
	v_add_u32_e32 v48, 0x90, v161
	v_mad_i64_i32 v[48:49], s[10:11], v48, s61, v[164:165]
	v_lshl_add_u64 v[48:49], v[48:49], 0, v[166:167]
; __device__ __forceinline__ unsigned cvt_pk_bf16(float lo, float hi) { unsigned r; asm volatile("v_cvt_pk_bf16_f32 %0, %1, %2" : "=v"(r) : "v"(lo), "v"(hi)); return r; }
;     __device__ __forceinline__ void pre(const Unit& u, int wr, int fr, float (&rv)[8]) const {
; #pragma unroll
;         for (int i = 0; i < 8; ++i) rv[i] = rs[u.pm * BM + wr * 64 + fr + (i >> 2) * HALF + (i & 3) * 16];
;     }
;     __device__ __forceinline__ void operator()(const f32x4 (&acc)[2][2][4][2], const Unit& u, int wr, int wc, int fr, int fq, const float (&rv)[8]) const {
;     ...
;         for (int ai = 0; ai < 2; ++ai)
; #pragma unroll
;             for (int m = 0; m < 4; ++m) {
;                 bf16_t* rowp = O + (size_t)(row0 + ai * HALF + m * 16) * ldc + col0;
;                 const float r = rv[ai * 4 + m];
;                 const f32x4 g0 = acc[ai][0][m][0] * r, g1 = acc[ai][0][m][1] * r, u0 = acc[ai][1][m][0] * r, u1 = acc[ai][1][m][1] * r;
;                 u32x4 w;
;                 w.x = cvt_pk_bf16(silu_mul(g0[0], u0[0]), silu_mul(g0[1], u0[1]));
;                 w.y = cvt_pk_bf16(silu_mul(g0[2], u0[2]), silu_mul(g0[3], u0[3]));
;                 w.z = cvt_pk_bf16(silu_mul(g1[0], u1[0]), silu_mul(g1[1], u1[1]));
;                 w.w = cvt_pk_bf16(silu_mul(g1[2], u1[2]), silu_mul(g1[3], u1[3]));
;                 *(u32x4*)rowp = w;
;             }
	v_pk_mul_f32 v[40:41], v[152:153], v[40:41] op_sel_hi:[0,1]
	v_pk_mul_f32 v[32:33], v[152:153], v[32:33] op_sel_hi:[0,1]
	v_pk_mul_f32 v[42:43], v[152:153], v[42:43] op_sel_hi:[0,1]
	v_pk_mul_f32 v[34:35], v[152:153], v[34:35] op_sel_hi:[0,1]
	v_pk_mul_f32 v[246:247], v[40:41], s[98:99]
	v_pk_mul_f32 v[248:249], v[42:43], s[98:99]
	v_exp_f32_e32 v246, v246
	v_exp_f32_e32 v247, v247
	v_exp_f32_e32 v248, v248
	v_exp_f32_e32 v249, v249
	v_pk_add_f32 v[246:247], v[246:247], s[100:101]
	v_pk_add_f32 v[248:249], v[248:249], s[100:101]
	v_rcp_f32_e32 v246, v246
	v_rcp_f32_e32 v247, v247
	v_rcp_f32_e32 v248, v248
	v_rcp_f32_e32 v249, v249
	v_pk_mul_f32 v[40:41], v[40:41], v[246:247]
	v_pk_mul_f32 v[42:43], v[42:43], v[248:249]
	v_pk_mul_f32 v[40:41], v[40:41], v[32:33]
	v_pk_mul_f32 v[42:43], v[42:43], v[34:35]
	v_cvt_pk_bf16_f32 v32, v44, v45
	v_cvt_pk_bf16_f32 v33, v46, v47
	v_cvt_pk_bf16_f32 v34, v40, v41
	v_cvt_pk_bf16_f32 v35, v42, v43
	global_store_dwordx4 v[48:49], v[32:35], off
	v_pk_mul_f32 v[28:29], v[146:147], v[28:29] op_sel_hi:[0,1]
	v_pk_mul_f32 v[20:21], v[146:147], v[20:21] op_sel_hi:[0,1]
	v_pk_mul_f32 v[30:31], v[146:147], v[30:31] op_sel_hi:[0,1]
	v_pk_mul_f32 v[22:23], v[146:147], v[22:23] op_sel_hi:[0,1]
	v_pk_mul_f32 v[246:247], v[28:29], s[98:99]
	v_pk_mul_f32 v[248:249], v[30:31], s[98:99]
	v_exp_f32_e32 v246, v246
	v_exp_f32_e32 v247, v247
	v_exp_f32_e32 v248, v248
	v_exp_f32_e32 v249, v249
	v_pk_add_f32 v[246:247], v[246:247], s[100:101]
	v_pk_add_f32 v[248:249], v[248:249], s[100:101]
	v_rcp_f32_e32 v246, v246
	v_rcp_f32_e32 v247, v247
	v_rcp_f32_e32 v248, v248
	v_rcp_f32_e32 v249, v249
	v_pk_mul_f32 v[28:29], v[28:29], v[246:247]
	v_pk_mul_f32 v[30:31], v[30:31], v[248:249]
	v_pk_mul_f32 v[28:29], v[28:29], v[20:21]
	v_pk_mul_f32 v[30:31], v[30:31], v[22:23]
	v_add_u32_e32 v32, 0xa0, v161
	v_mad_i64_i32 v[32:33], s[10:11], v32, s61, v[164:165]
	v_lshl_add_u64 v[32:33], v[32:33], 0, v[166:167]
	v_pk_mul_f32 v[24:25], v[146:147], v[24:25] op_sel_hi:[0,1]
	v_pk_mul_f32 v[16:17], v[146:147], v[16:17] op_sel_hi:[0,1]
	v_pk_mul_f32 v[26:27], v[146:147], v[26:27] op_sel_hi:[0,1]
	v_pk_mul_f32 v[18:19], v[146:147], v[18:19] op_sel_hi:[0,1]
	v_pk_mul_f32 v[246:247], v[24:25], s[98:99]
	v_pk_mul_f32 v[248:249], v[26:27], s[98:99]
	v_exp_f32_e32 v246, v246
	v_exp_f32_e32 v247, v247
	v_exp_f32_e32 v248, v248
	v_exp_f32_e32 v249, v249
	v_pk_add_f32 v[246:247], v[246:247], s[100:101]
	v_pk_add_f32 v[248:249], v[248:249], s[100:101]
	v_rcp_f32_e32 v246, v246
	v_rcp_f32_e32 v247, v247
	v_rcp_f32_e32 v248, v248
	v_rcp_f32_e32 v249, v249
	v_pk_mul_f32 v[24:25], v[24:25], v[246:247]
	v_pk_mul_f32 v[26:27], v[26:27], v[248:249]
	v_pk_mul_f32 v[24:25], v[24:25], v[16:17]
	v_pk_mul_f32 v[26:27], v[26:27], v[18:19]
	v_cvt_pk_bf16_f32 v16, v28, v29
	v_cvt_pk_bf16_f32 v17, v30, v31
	v_cvt_pk_bf16_f32 v18, v24, v25
	v_cvt_pk_bf16_f32 v19, v26, v27
	global_store_dwordx4 v[32:33], v[16:19], off
	v_pk_mul_f32 v[12:13], v[136:137], v[12:13] op_sel_hi:[0,1]
	v_pk_mul_f32 v[4:5], v[136:137], v[4:5] op_sel_hi:[0,1]
	v_pk_mul_f32 v[14:15], v[136:137], v[14:15] op_sel_hi:[0,1]
	v_pk_mul_f32 v[6:7], v[136:137], v[6:7] op_sel_hi:[0,1]
	v_pk_mul_f32 v[246:247], v[12:13], s[98:99]
	v_pk_mul_f32 v[248:249], v[14:15], s[98:99]
	v_exp_f32_e32 v246, v246
	v_exp_f32_e32 v247, v247
	v_exp_f32_e32 v248, v248
	v_exp_f32_e32 v249, v249
	v_pk_add_f32 v[246:247], v[246:247], s[100:101]
	v_pk_add_f32 v[248:249], v[248:249], s[100:101]
	v_rcp_f32_e32 v246, v246
	v_rcp_f32_e32 v247, v247
	v_rcp_f32_e32 v248, v248
	v_rcp_f32_e32 v249, v249
	v_pk_mul_f32 v[12:13], v[12:13], v[246:247]
	v_pk_mul_f32 v[14:15], v[14:15], v[248:249]
	v_pk_mul_f32 v[12:13], v[12:13], v[4:5]
	v_pk_mul_f32 v[14:15], v[14:15], v[6:7]
	v_add_u32_e32 v16, 0xb0, v161
	v_mad_i64_i32 v[16:17], s[10:11], v16, s61, v[164:165]
	v_lshl_add_u64 v[16:17], v[16:17], 0, v[166:167]
	s_andn2_b64 vcc, exec, s[0:1]
	s_mov_b64 s[0:1], -1
	v_pk_mul_f32 v[8:9], v[136:137], v[8:9] op_sel_hi:[0,1]
	v_pk_mul_f32 v[0:1], v[136:137], v[0:1] op_sel_hi:[0,1]
	v_pk_mul_f32 v[10:11], v[136:137], v[10:11] op_sel_hi:[0,1]
	v_pk_mul_f32 v[2:3], v[136:137], v[2:3] op_sel_hi:[0,1]
	v_pk_mul_f32 v[246:247], v[8:9], s[98:99]
	v_pk_mul_f32 v[248:249], v[10:11], s[98:99]
	v_exp_f32_e32 v246, v246
	v_exp_f32_e32 v247, v247
	v_exp_f32_e32 v248, v248
	v_exp_f32_e32 v249, v249
	v_pk_add_f32 v[246:247], v[246:247], s[100:101]
	v_pk_add_f32 v[248:249], v[248:249], s[100:101]
	v_rcp_f32_e32 v246, v246
	v_rcp_f32_e32 v247, v247
	v_rcp_f32_e32 v248, v248
	v_rcp_f32_e32 v249, v249
	v_pk_mul_f32 v[8:9], v[8:9], v[246:247]
	v_pk_mul_f32 v[10:11], v[10:11], v[248:249]
	v_pk_mul_f32 v[8:9], v[8:9], v[0:1]
	v_pk_mul_f32 v[10:11], v[10:11], v[2:3]
	v_cvt_pk_bf16_f32 v0, v12, v13
	v_cvt_pk_bf16_f32 v1, v14, v15
	v_cvt_pk_bf16_f32 v2, v8, v9
	v_cvt_pk_bf16_f32 v3, v10, v11
	global_store_dwordx4 v[16:17], v[0:3], off
	s_cbranch_vccnz .LBB0_696
	s_nop 0
	v_lshl_add_u32 v0, s36, 8, v137
	v_ashrrev_i32_e32 v1, 31, v0
	v_lshl_add_u64 v[0:1], v[0:1], 2, s[16:17]
	global_load_dword v162, v[0:1], off
	global_load_dword v160, v[0:1], off offset:64
	global_load_dword v158, v[0:1], off offset:128
	global_load_dword v156, v[0:1], off offset:192
	global_load_dword v154, v[0:1], off offset:512
	global_load_dword v152, v[0:1], off offset:576
	global_load_dword v146, v[0:1], off offset:640
	global_load_dword v136, v[0:1], off offset:704
	s_andn2_b64 vcc, exec, s[4:5]
	s_cbranch_vccnz .LBB0_695
	s_barrier
	s_branch .LBB0_695
